# W4/W5/W6 bf16 copies and PB=bf16(p) moved from the P0 prologue into the idle workgroups of the FFN gate/up phase last round (hand-written streaming code)
# speedup vs baseline: 1.0480x; 1.0037x over previous
; __device__ __forceinline__ unsigned cvt_pk_bf16(float lo, float hi) { unsigned r; asm volatile("v_cvt_pk_bf16_f32 %0, %1, %2" : "=v"(r) : "v"(lo), "v"(hi)); return r; }
; __device__ __forceinline__ void tr_store(const TrItem& t, int lane, const f32x4 (&v)[8], const f32x4 (&g)[2]) {
;     const int r = lane & 7, k0 = 64 * t.kb + 8 * (lane >> 3); bf16_t* dst = t.WT + (size_t)(t.dr0 + 4 * r) * t.K + k0;
; #pragma unroll
;     for (int j = 0; j < 4; ++j) { u32x4 o; o.x = cvt_pk_bf16(v[0][j] * g[0][0], v[1][j] * g[0][1]); o.y = cvt_pk_bf16(v[2][j] * g[0][2], v[3][j] * g[0][3]);
;         o.z = cvt_pk_bf16(v[4][j] * g[1][0], v[5][j] * g[1][1]); o.w = cvt_pk_bf16(v[6][j] * g[1][2], v[7][j] * g[1][3]); *(u32x4*)(dst + (size_t)j * t.K) = o; }
; }
; __device__ __forceinline__ void p0_prologue(const Params& p, unsigned char* lds) {
;     const int tid = threadIdx.x, lane = tid & 63, wave = tid >> 6, G = gridDim.x;
;     const int gw = blockIdx.x * 8 + wave, NGW = G * 8;
;     unsigned char* ws = p.ws;
;     constexpr int NITEMS = (DM / 64) * (DIN / 32) + 2 * (DM / 64) * (DM / 32) + (DM / 64) * (2 * DFF / 32) + (DFF / 64) * (DM / 32) + (DPLE / 64) * (DM / 32);
;     for (int it = gw; it < NITEMS; it += 2 * NGW) {
;         const int it1 = it + NGW < NITEMS ? it + NGW : it;
;         TrItem t0, t1; tr_decode(p, it, t0); tr_decode(p, it1, t1);
;         f32x4 v0[8], v1[8], g0[2], g1[2];
;         tr_load(t0, lane, v0, g0); tr_load(t1, lane, v1, g1);
;         tr_store(t0, lane, v0, g0); tr_store(t1, lane, v1, g1);
;     }
.LBB0_19:
	s_or_b64 exec, exec, s[4:5]
	v_lshrrev_b32_e32 v0, 6, v176
	s_lshl_b32 s95, s2, 3
	v_add_u32_e32 v81, s95, v0
	s_movk_i32 s0, 0x1b00
	s_cmp_eq_u32 s66, 0x100
	s_cselect_b32 s0, 0x1300, s0
	s_lshl_b32 s94, s66, 3
	v_cmp_gt_i32_e32 vcc, s0, v81
	s_and_saveexec_b64 s[4:5], vcc
	s_cbranch_execz .LBB0_74
	s_lshl_b32 s1, s66, 4
	s_add_u32 s6, s64, 0x1a80000
	s_addc_u32 s7, s65, 0
	s_add_u32 s8, s64, 0x1880000
	s_addc_u32 s9, s65, 0
	s_add_u32 s10, s64, 0x1300000
	s_addc_u32 s11, s65, 0
	s_add_u32 s12, s64, 0x800000
	v_lshlrev_b32_e32 v1, 2, v176
	s_addc_u32 s13, s65, 0
	v_and_b32_e32 v80, 28, v1
	s_add_u32 s14, s64, 0x600000
	v_lshlrev_b32_e32 v0, 5, v0
	s_mov_b32 s18, 0x76981032
	v_and_b32_e32 v85, 56, v176
	v_mov_b32_e32 v83, 0
	s_addc_u32 s15, s65, 0
	v_lshl_add_u32 v84, s2, 8, v0
	s_lshl_b32 s3, s66, 9
	s_mov_b64 s[16:17], 0
	s_movk_i32 s30, 0x5ff
	s_movk_i32 s31, 0x7ff
	s_movk_i32 s33, 0x12ff
	s_movk_i32 s34, 0x187f
	s_movk_i32 s35, 0x1a7f
	s_movk_i32 s52, 0x60
	s_movk_i32 s53, 0xf80
	s_mov_b32 s54, 0x2aaaaaab
	s_mov_b32 s19, 0xba54
	s_movk_i32 s55, 0x800
	v_lshlrev_b32_e32 v82, 2, v80
	v_mov_b32_e32 v86, v81
	s_branch .LBB0_22
.LBB0_21:
	s_or_b64 exec, exec, s[20:21]
	v_or_b32_e32 v89, v88, v80
	v_ashrrev_i32_e32 v88, 31, v88
	v_mul_lo_u32 v98, v93, v89
	v_mul_lo_u32 v99, v92, v88
	v_mad_u64_u32 v[88:89], s[20:21], v92, v89, 0
	v_add3_u32 v89, v89, v99, v98
	v_lshl_add_u64 v[88:89], v[88:89], 1, v[90:91]
	s_waitcnt vmcnt(9)
	v_mul_f32_e32 v12, v12, v68
	v_lshl_add_u64 v[98:99], v[100:101], 1, v[88:89]
	v_mul_f32_e32 v16, v16, v69
	v_cvt_pk_bf16_f32 v88, v12, v16
	v_mul_f32_e32 v12, v28, v70
	v_mul_f32_e32 v16, v32, v71
	v_cvt_pk_bf16_f32 v89, v12, v16
	s_waitcnt vmcnt(8)
	v_mul_f32_e32 v12, v44, v76
	v_mul_f32_e32 v16, v48, v77
	v_cvt_pk_bf16_f32 v90, v12, v16
	v_mul_f32_e32 v12, v60, v78
	v_mul_f32_e32 v16, v64, v79
	v_cvt_pk_bf16_f32 v91, v12, v16
	v_mul_f32_e32 v12, v13, v68
	v_mul_f32_e32 v13, v17, v69
	global_store_dwordx4 v[98:99], v[88:91], off
	v_lshlrev_b64 v[16:17], 1, v[92:93]
	v_mul_f32_e32 v14, v14, v68
	v_cvt_pk_bf16_f32 v88, v12, v13
	v_mul_f32_e32 v12, v29, v70
	v_mul_f32_e32 v13, v33, v71
	v_cvt_pk_bf16_f32 v89, v12, v13
	v_mul_f32_e32 v12, v45, v76
	v_mul_f32_e32 v13, v49, v77
	v_cvt_pk_bf16_f32 v90, v12, v13
	v_mul_f32_e32 v12, v61, v78
	v_mul_f32_e32 v13, v65, v79
	v_cvt_pk_bf16_f32 v91, v12, v13
	v_lshl_add_u64 v[12:13], v[98:99], 0, v[16:17]
	global_store_dwordx4 v[12:13], v[88:91], off
	v_mul_f32_e32 v18, v18, v69
	v_lshl_add_u64 v[28:29], v[12:13], 0, v[16:17]
	v_cvt_pk_bf16_f32 v88, v14, v18
	v_mul_f32_e32 v14, v30, v70
	v_mul_f32_e32 v18, v34, v71
	v_cvt_pk_bf16_f32 v89, v14, v18
	v_mul_f32_e32 v14, v46, v76
	v_mul_f32_e32 v18, v50, v77
	v_cvt_pk_bf16_f32 v90, v14, v18
	v_mul_f32_e32 v14, v62, v78
	v_mul_f32_e32 v12, v15, v68
	v_mul_f32_e32 v13, v19, v69
	v_mul_f32_e32 v18, v66, v79
	v_cvt_pk_bf16_f32 v91, v14, v18
	global_store_dwordx4 v[28:29], v[88:91], off
	v_cvt_pk_bf16_f32 v12, v12, v13
	v_mul_f32_e32 v13, v31, v70
	v_mul_f32_e32 v14, v35, v71
	v_cvt_pk_bf16_f32 v13, v13, v14
	v_mul_f32_e32 v14, v47, v76
	v_mul_f32_e32 v15, v51, v77
	v_cvt_pk_bf16_f32 v14, v14, v15
	v_mul_f32_e32 v15, v63, v78
	v_lshl_add_u64 v[16:17], v[28:29], 0, v[16:17]
	v_mul_f32_e32 v18, v67, v79
	v_cvt_pk_bf16_f32 v15, v15, v18
	global_store_dwordx4 v[16:17], v[12:15], off
	s_waitcnt vmcnt(5)
	v_mul_f32_e32 v4, v4, v0
	v_mul_f32_e32 v8, v8, v1
	v_or_b32_e32 v12, v87, v80
	v_ashrrev_i32_e32 v13, 31, v87
	v_mul_lo_u32 v14, v97, v12
	v_mul_lo_u32 v15, v96, v13
	v_mad_u64_u32 v[12:13], s[20:21], v96, v12, 0
	v_add3_u32 v13, v13, v15, v14
	v_lshl_add_u64 v[12:13], v[12:13], 1, v[94:95]
	v_lshl_add_u64 v[16:17], v[102:103], 1, v[12:13]
	v_cvt_pk_bf16_f32 v12, v4, v8
	v_mul_f32_e32 v4, v20, v2
	v_mul_f32_e32 v8, v24, v3
	v_cvt_pk_bf16_f32 v13, v4, v8
	s_waitcnt vmcnt(4)
	v_mul_f32_e32 v4, v36, v72
	v_mul_f32_e32 v8, v40, v73
	v_cvt_pk_bf16_f32 v14, v4, v8
	v_mul_f32_e32 v4, v52, v74
	v_mul_f32_e32 v8, v56, v75
	v_cvt_pk_bf16_f32 v15, v4, v8
	v_mul_f32_e32 v4, v5, v0
	v_mul_f32_e32 v5, v9, v1
	global_store_dwordx4 v[16:17], v[12:15], off
	v_mul_f32_e32 v6, v6, v0
	v_mul_f32_e32 v10, v10, v1
	v_cvt_pk_bf16_f32 v12, v4, v5
	v_mul_f32_e32 v4, v21, v2
	v_mul_f32_e32 v5, v25, v3
	v_cvt_pk_bf16_f32 v13, v4, v5
	v_mul_f32_e32 v4, v37, v72
	v_mul_f32_e32 v5, v41, v73
	v_cvt_pk_bf16_f32 v14, v4, v5
	v_mul_f32_e32 v4, v53, v74
	v_mul_f32_e32 v5, v57, v75
	v_cvt_pk_bf16_f32 v15, v4, v5
	v_lshlrev_b64 v[4:5], 1, v[96:97]
	v_lshl_add_u64 v[8:9], v[16:17], 0, v[4:5]
	global_store_dwordx4 v[8:9], v[12:15], off
	v_lshl_add_u64 v[8:9], v[8:9], 0, v[4:5]
	v_mul_f32_e32 v0, v7, v0
	v_cvt_pk_bf16_f32 v12, v6, v10
	v_mul_f32_e32 v6, v22, v2
	v_mul_f32_e32 v10, v26, v3
	v_cvt_pk_bf16_f32 v13, v6, v10
	v_mul_f32_e32 v6, v38, v72
	v_mul_f32_e32 v10, v42, v73
	v_mul_f32_e32 v1, v11, v1
	v_cvt_pk_bf16_f32 v14, v6, v10
	v_mul_f32_e32 v6, v54, v74
	v_mul_f32_e32 v10, v58, v75
	v_cvt_pk_bf16_f32 v15, v6, v10
	global_store_dwordx4 v[8:9], v[12:15], off
	v_cvt_pk_bf16_f32 v0, v0, v1
	v_mul_f32_e32 v1, v23, v2
	v_mul_f32_e32 v2, v27, v3
	v_add_u32_e32 v86, s1, v86
	s_nop 0
	v_cvt_pk_bf16_f32 v1, v1, v2
	v_mul_f32_e32 v2, v39, v72
	v_mul_f32_e32 v3, v43, v73
	v_cmp_le_i32_e32 vcc, s0, v86
	v_cvt_pk_bf16_f32 v2, v2, v3
	v_mul_f32_e32 v3, v55, v74
	v_lshl_add_u64 v[4:5], v[8:9], 0, v[4:5]
	s_or_b64 s[16:17], vcc, s[16:17]
	v_add_u32_e32 v84, s3, v84
	v_mul_f32_e32 v6, v59, v75
	v_cvt_pk_bf16_f32 v3, v3, v6
	global_store_dwordx4 v[4:5], v[0:3], off
	s_andn2_b64 exec, exec, s[16:17]
	s_cbranch_execz .LBB0_74

; __device__ __forceinline__ unsigned cvt_pk_bf16(float lo, float hi) { unsigned r; asm volatile("v_cvt_pk_bf16_f32 %0, %1, %2" : "=v"(r) : "v"(lo), "v"(hi)); return r; }
; __device__ __forceinline__ void p0_prologue(const Params& p, unsigned char* lds) {
;     ...
;     const size_t gt = (size_t)blockIdx.x * 512 + tid, NT = (size_t)G * 512;
;     { bf16_t* PB = (bf16_t*)(ws + WS_PB); constexpr size_t NPB = (size_t)MT * DPLE / 8;
;       for (size_t i0 = gt; i0 < NPB; i0 += 4 * NT) { f32x4 a[4], b[4]; size_t e[4];
; #pragma unroll
;           for (int q = 0; q < 4; ++q) { const size_t i = i0 + q * NT < NPB ? i0 + q * NT : i0; e[q] = i * 8; const float* s = e[q] < (size_t)MP * DPLE ? p.in[I_PP] + e[q] : p.in[I_PS] + (e[q] - (size_t)MP * DPLE);
;               a[q] = __builtin_nontemporal_load((const f32x4*)s); b[q] = __builtin_nontemporal_load((const f32x4*)(s + 4)); }
; #pragma unroll
;           for (int q = 0; q < 4; ++q) { u32x4 w; w.x = cvt_pk_bf16(a[q][0], a[q][1]); w.y = cvt_pk_bf16(a[q][2], a[q][3]); w.z = cvt_pk_bf16(b[q][0], b[q][1]); w.w = cvt_pk_bf16(b[q][2], b[q][3]); *(u32x4*)(PB + e[q]) = w; } } }
.LBB0_79:
	s_or_b64 exec, exec, s[6:7]
	s_mov_b32 s3, 0
	s_ashr_i32 s87, s66, 31
	s_mov_b32 s86, s66
	s_lshl_b64 s[0:1], s[2:3], 9
	v_mov_b32_e32 v177, 0
	s_lshl_b64 s[4:5], s[86:87], 9
	v_lshl_add_u64 v[0:1], s[0:1], 0, v[176:177]
	s_add_u32 s52, s64, 0x1b35e00
	s_mov_b64 s[6:7], 0x84000
	s_mov_b64 s[16:17], 0x1b35e00
	s_addc_u32 s53, s65, 0
	v_cmp_gt_u64_e32 vcc, s[6:7], v[0:1]
	s_and_saveexec_b64 s[8:9], vcc
	v_readlane_b32 s36, v247, 0
	v_readlane_b32 s40, v247, 4
	v_readlane_b32 s41, v247, 5
	v_readlane_b32 s42, v247, 6
	v_readlane_b32 s43, v247, 7
	v_readlane_b32 s37, v247, 1
	v_readlane_b32 s38, v247, 2
	v_readlane_b32 s39, v247, 3
	v_readlane_b32 s44, v247, 8
	v_readlane_b32 s45, v247, 9
	v_readlane_b32 s46, v247, 10
	v_readlane_b32 s47, v247, 11
	v_readlane_b32 s48, v247, 12
	v_readlane_b32 s49, v247, 13
	v_readlane_b32 s50, v247, 14
	v_readlane_b32 s51, v247, 15
	s_cmp_eq_u32 s66, 0x100
	s_cbranch_scc1 .LBB0_82
	s_cbranch_execz .LBB0_82
	s_add_u32 s12, s42, 0xff000000
	s_addc_u32 s13, s43, -1
	s_lshl_b64 s[0:1], s[2:3], 14
	v_lshlrev_b64 v[2:3], 5, v[176:177]
	v_lshl_add_u64 v[2:3], s[0:1], 0, v[2:3]
	s_lshl_b64 s[14:15], s[86:87], 16
	s_lshl_b64 s[0:1], s[2:3], 13
	s_add_u32 s0, s64, s0
	s_addc_u32 s1, s65, s1
	s_mov_b32 s10, 0xff000000
	v_lshl_add_u64 v[4:5], v[176:177], 4, s[0:1]
	s_mov_b32 s11, -1
	v_lshl_add_u64 v[4:5], v[4:5], 0, s[16:17]
	s_lshl_b64 s[16:17], s[86:87], 15
	s_mov_b64 s[18:19], 0
	s_mov_b64 s[20:21], 0x80000
	s_mov_b64 s[22:23], 0x83fff
	v_mov_b64_e32 v[6:7], v[0:1]

; __host__ __device__ __forceinline__ int permcol(int c) { return perm12(c >> 8) * 256 + (c & 255); }
; __device__ __forceinline__ void tr_decode(const Params& p, int r, TrItem& t) {
;     constexpr int I1 = (DM / 64) * (DIN / 32), I2 = (DM / 64) * (DM / 32), I3 = (DM / 64) * (2 * DFF / 32), I4 = (DFF / 64) * (DM / 32), I5 = I2;
;     unsigned char* ws = p.ws; t.gain = nullptr;
;     if (r < I1) { const int nb = r % (DIN / 32), n0p = nb * 32, n0 = permcol(n0p); t.kb = r / (DIN / 32);
;         if (n0 < 2048) t.sc0 = n0; else { const int n1 = n0 - 2048, tt = n1 >> 8, w = n1 & 255; t.sc0 = 2048 + (w >> 7) * 512 + tt * 128 + (w & 127); }
;         t.W = p.in[I_WIN]; t.ldw = DIN; t.K = DM; t.WT = (bf16_t*)(ws + WS_W1); t.dr0 = n0p; return; } r -= I1;
;     if (r < I2) { const int nb = r % (DM / 32); t.kb = r / (DM / 32); t.W = p.in[I_WOUT]; t.ldw = DM; t.K = DM; t.sc0 = nb * 32; t.WT = (bf16_t*)(ws + WS_W2); t.dr0 = nb * 32; return; } r -= I2;
;     if (r < I3) { const int nb = r % (2 * DFF / 32), n0 = nb * 32, tt = n0 >> 8, w = n0 & 255; t.kb = r / (2 * DFF / 32);
;         t.W = (w >> 7) ? p.in[I_WU] : p.in[I_WG]; t.ldw = DFF; t.K = DM; t.sc0 = tt * 128 + (w & 127); t.gain = p.in[I_NFFN]; t.WT = (bf16_t*)(ws + WS_W3); t.dr0 = n0; return; } r -= I3;
;     if (r < I4) { const int nb = r % (DM / 32); t.kb = r / (DM / 32); t.W = p.in[I_WD]; t.ldw = DM; t.K = DFF; t.sc0 = nb * 32; t.WT = (bf16_t*)(ws + WS_W4); t.dr0 = nb * 32; return; } r -= I4;
; __device__ __forceinline__ void p0_prologue(const Params& p, unsigned char* lds) {
;     ...
;     { bf16_t* PB = (bf16_t*)(ws + WS_PB); constexpr size_t NPB = (size_t)MT * DPLE / 8;
;       for (size_t i0 = gt; i0 < NPB; i0 += 4 * NT) { f32x4 a[4], b[4]; size_t e[4];
; #pragma unroll
;           for (int q = 0; q < 4; ++q) { const size_t i = i0 + q * NT < NPB ? i0 + q * NT : i0; e[q] = i * 8; const float* s = e[q] < (size_t)MP * DPLE ? p.in[I_PP] + e[q] : p.in[I_PS] + (e[q] - (size_t)MP * DPLE);
;               a[q] = __builtin_nontemporal_load((const f32x4*)s); b[q] = __builtin_nontemporal_load((const f32x4*)(s + 4)); }
; #pragma unroll
;           for (int q = 0; q < 4; ++q) { u32x4 w; w.x = cvt_pk_bf16(a[q][0], a[q][1]); w.y = cvt_pk_bf16(a[q][2], a[q][3]); w.z = cvt_pk_bf16(b[q][0], b[q][1]); w.w = cvt_pk_bf16(b[q][2], b[q][3]); *(u32x4*)(PB + e[q]) = w; } } }
.LBB0_708:
	s_cmp_lg_u32 s66, 0x100
	s_cbranch_scc1 .Ltail_done
	s_cmp_lt_u32 s2, 172
	s_cbranch_scc1 .Ltail_done
	s_sub_u32 s0, s2, 172
	v_readfirstlane_b32 s1, v176
	s_nop 3
	s_lshr_b32 s1, s1, 6
	s_lshl_b32 s3, s0, 3
	s_add_u32 s3, s3, s1
	v_lshlrev_b32_e32 v120, 5, v206
	v_lshlrev_b32_e32 v121, 4, v206
	v_readlane_b32 s4, v247, 4
	v_readlane_b32 s5, v247, 5
	v_readlane_b32 s6, v247, 6
	v_readlane_b32 s7, v247, 7
	s_add_u32 s8, s64, 0x1b35e00
	s_addc_u32 s9, s65, 0
	s_mul_i32 s10, s3, 12
	s_min_u32 s11, s3, 0x180
	s_add_u32 s10, s10, s11
	s_mov_b32 s11, 3
.Ltail_pb4:
	s_add_u32 s39, s10, 0
	s_cmp_lt_u32 s39, 0x2000
	s_cselect_b32 s12, s4, s6
	s_cselect_b32 s13, s5, s7
	s_cselect_b32 s38, 0, 0x2000
	s_sub_u32 s38, s39, s38
	s_lshl_b32 s38, s38, 11
	s_add_u32 s12, s12, s38
	s_addc_u32 s13, s13, 0
	global_load_dwordx4 v[0:3], v120, s[12:13]
	global_load_dwordx4 v[4:7], v120, s[12:13] offset:16
	s_add_u32 s39, s10, 1
	s_cmp_lt_u32 s39, 0x2000
	s_cselect_b32 s14, s4, s6
	s_cselect_b32 s15, s5, s7
	s_cselect_b32 s38, 0, 0x2000
	s_sub_u32 s38, s39, s38
	s_lshl_b32 s38, s38, 11
	s_add_u32 s14, s14, s38
	s_addc_u32 s15, s15, 0
	global_load_dwordx4 v[8:11], v120, s[14:15]
	global_load_dwordx4 v[12:15], v120, s[14:15] offset:16
	s_add_u32 s39, s10, 2
	s_cmp_lt_u32 s39, 0x2000
	s_cselect_b32 s32, s4, s6
	s_cselect_b32 s33, s5, s7
	s_cselect_b32 s38, 0, 0x2000
	s_sub_u32 s38, s39, s38
	s_lshl_b32 s38, s38, 11
	s_add_u32 s32, s32, s38
	s_addc_u32 s33, s33, 0
	global_load_dwordx4 v[16:19], v120, s[32:33]
	global_load_dwordx4 v[20:23], v120, s[32:33] offset:16
	s_add_u32 s39, s10, 3
	s_cmp_lt_u32 s39, 0x2000
	s_cselect_b32 s36, s4, s6
	s_cselect_b32 s37, s5, s7
	s_cselect_b32 s38, 0, 0x2000
	s_sub_u32 s38, s39, s38
	s_lshl_b32 s38, s38, 11
	s_add_u32 s36, s36, s38
	s_addc_u32 s37, s37, 0
	global_load_dwordx4 v[24:27], v120, s[36:37]
	global_load_dwordx4 v[28:31], v120, s[36:37] offset:16
	s_add_u32 s39, s10, 0
	s_waitcnt vmcnt(6)
	v_cvt_pk_bf16_f32 v0, v0, v1
	v_cvt_pk_bf16_f32 v1, v2, v3
	v_cvt_pk_bf16_f32 v2, v4, v5
	v_cvt_pk_bf16_f32 v3, v6, v7
	s_lshl_b32 s38, s39, 10
	s_add_u32 s40, s8, s38
	s_addc_u32 s41, s9, 0
	global_store_dwordx4 v121, v[0:3], s[40:41]
	s_add_u32 s39, s10, 1
	s_waitcnt vmcnt(5)
	v_cvt_pk_bf16_f32 v8, v8, v9
	v_cvt_pk_bf16_f32 v9, v10, v11
	v_cvt_pk_bf16_f32 v10, v12, v13
	v_cvt_pk_bf16_f32 v11, v14, v15
	s_lshl_b32 s38, s39, 10
	s_add_u32 s40, s8, s38
	s_addc_u32 s41, s9, 0
	global_store_dwordx4 v121, v[8:11], s[40:41]
	s_add_u32 s39, s10, 2
	s_waitcnt vmcnt(4)
	v_cvt_pk_bf16_f32 v16, v16, v17
	v_cvt_pk_bf16_f32 v17, v18, v19
	v_cvt_pk_bf16_f32 v18, v20, v21
	v_cvt_pk_bf16_f32 v19, v22, v23
	s_lshl_b32 s38, s39, 10
	s_add_u32 s40, s8, s38
	s_addc_u32 s41, s9, 0
	global_store_dwordx4 v121, v[16:19], s[40:41]
	s_add_u32 s39, s10, 3
	s_waitcnt vmcnt(3)
	v_cvt_pk_bf16_f32 v24, v24, v25
	v_cvt_pk_bf16_f32 v25, v26, v27
	v_cvt_pk_bf16_f32 v26, v28, v29
	v_cvt_pk_bf16_f32 v27, v30, v31
	s_lshl_b32 s38, s39, 10
	s_add_u32 s40, s8, s38
	s_addc_u32 s41, s9, 0
	global_store_dwordx4 v121, v[24:27], s[40:41]
	s_add_u32 s10, s10, 4
	s_sub_u32 s11, s11, 1
	s_cmp_lg_u32 s11, 0
	s_cbranch_scc1 .Ltail_pb4
	s_cmp_ge_u32 s3, 0x180
	s_cbranch_scc1 .Ltail_pb_done
	s_cmp_lt_u32 s10, 0x2000
	s_cselect_b32 s12, s4, s6
	s_cselect_b32 s13, s5, s7
	s_cselect_b32 s38, 0, 0x2000
	s_sub_u32 s38, s10, s38
	s_lshl_b32 s38, s38, 11
	s_add_u32 s12, s12, s38
	s_addc_u32 s13, s13, 0
	global_load_dwordx4 v[0:3], v120, s[12:13]
	global_load_dwordx4 v[4:7], v120, s[12:13] offset:16
	s_waitcnt vmcnt(0)
	v_cvt_pk_bf16_f32 v0, v0, v1
	v_cvt_pk_bf16_f32 v1, v2, v3
	v_cvt_pk_bf16_f32 v2, v4, v5
	v_cvt_pk_bf16_f32 v3, v6, v7
	s_lshl_b32 s38, s10, 10
	s_add_u32 s40, s8, s38
	s_addc_u32 s41, s9, 0
	global_store_dwordx4 v121, v[0:3], s[40:41]
.Ltail_pb_done:
	v_readlane_b32 s4, v247, 20
	v_readlane_b32 s5, v247, 21
	v_readlane_b32 s6, v247, 22
	v_readlane_b32 s7, v247, 23
	v_readlane_b32 s8, v247, 24
	v_readlane_b32 s9, v247, 25
	v_readlane_b32 s10, v247, 26
	v_readlane_b32 s11, v247, 27
	v_and_b32_e32 v122, 7, v206
	v_lshrrev_b32_e32 v123, 3, v206
	v_lshlrev_b32_e32 v124, 15, v123
	v_lshl_add_u32 v124, v122, 4, v124
	v_add_u32_e32 v125, 0x1000, v124
	v_add_u32_e32 v126, 0x2000, v124
	v_add_u32_e32 v127, 0x3000, v124
	v_add_u32_e32 v128, 0x4000, v124
	v_add_u32_e32 v129, 0x5000, v124
	v_add_u32_e32 v130, 0x6000, v124
	v_add_u32_e32 v131, 0x7000, v124
	s_mov_b32 s39, s3
.Ltail_w:
	s_cmp_gt_u32 s39, 0x7ff
	s_cbranch_scc1 .Ltail_w_done
	s_cmp_lt_u32 s39, 0x580
	s_cbranch_scc0 .Ltail_w5
	s_mov_b32 s38, s39
	s_mov_b64 s[12:13], s[4:5]
	s_add_u32 s14, s64, 0x1300000
	s_addc_u32 s15, s65, 0
	s_movk_i32 s32, 0xb00
	s_mov_b32 s33, 0
	s_branch .Ltail_wgo
; __device__ __forceinline__ unsigned cvt_pk_bf16(float lo, float hi) { unsigned r; asm volatile("v_cvt_pk_bf16_f32 %0, %1, %2" : "=v"(r) : "v"(lo), "v"(hi)); return r; }
; __device__ __forceinline__ unsigned xb_add(unsigned* p, unsigned v) { return __hip_atomic_fetch_add(p, v, __ATOMIC_RELAXED, __HIP_MEMORY_SCOPE_AGENT); }
; __device__ __forceinline__ void xcd_barrier(const XcdBarrier& b) {
;     asm volatile("s_waitcnt vmcnt(0)" ::: "memory");
;     __syncthreads();
;     if (threadIdx.x == 0) {
;         unsigned* bar = b.bar;
;         __builtin_amdgcn_s_waitcnt(0);
;         unsigned nloc = b.st[0], nx = b.st[1];
;         if (nloc == 0u) { xcd_barrier_complete(bar, b.x, nloc, nx); b.st[0] = nloc; b.st[1] = nx; }
;         const unsigned old = xb_add(&bar[XB_XSUB(b.x)], 1u);
;         const unsigned gen = old / nloc;
; __device__ __forceinline__ void tr_load(const TrItem& t, int lane, f32x4 (&v)[8], f32x4 (&g)[2]) {
;     const int r = lane & 7, k0 = 64 * t.kb + 8 * (lane >> 3); const float* src = t.W + (size_t)k0 * t.ldw + t.sc0 + 4 * r;
; #pragma unroll
;     for (int i = 0; i < 8; ++i) v[i] = __builtin_nontemporal_load((const f32x4*)(src + (size_t)i * t.ldw));
;     if (t.gain) { g[0] = *(const f32x4*)(t.gain + k0); g[1] = *(const f32x4*)(t.gain + k0 + 4); } else { g[0] = (f32x4){1.f, 1.f, 1.f, 1.f}; g[1] = g[0]; }
; }
; __device__ __forceinline__ void tr_store(const TrItem& t, int lane, const f32x4 (&v)[8], const f32x4 (&g)[2]) {
;     const int r = lane & 7, k0 = 64 * t.kb + 8 * (lane >> 3); bf16_t* dst = t.WT + (size_t)(t.dr0 + 4 * r) * t.K + k0;
; #pragma unroll
;     for (int j = 0; j < 4; ++j) { u32x4 o; o.x = cvt_pk_bf16(v[0][j] * g[0][0], v[1][j] * g[0][1]); o.y = cvt_pk_bf16(v[2][j] * g[0][2], v[3][j] * g[0][3]);
;         o.z = cvt_pk_bf16(v[4][j] * g[1][0], v[5][j] * g[1][1]); o.w = cvt_pk_bf16(v[6][j] * g[1][2], v[7][j] * g[1][3]); *(u32x4*)(dst + (size_t)j * t.K) = o; }
; }
.Ltail_w5:
	s_cmp_lt_u32 s39, 0x780
	s_cbranch_scc0 .Ltail_w6
	s_sub_u32 s38, s39, 0x580
	s_mov_b64 s[12:13], s[8:9]
	s_add_u32 s14, s64, 0x1880000
	s_addc_u32 s15, s65, 0
	s_movk_i32 s32, 0x400
	s_mov_b32 s33, 1
	s_branch .Ltail_wgo
.Ltail_w6:
	s_sub_u32 s38, s39, 0x780
	s_mov_b64 s[12:13], s[10:11]
	s_add_u32 s14, s64, 0x1a80000
	s_addc_u32 s15, s65, 0
	s_movk_i32 s32, 0x100
	s_mov_b32 s33, 0
.Ltail_wgo:
	s_lshr_b32 s36, s38, 5
	s_and_b32 s37, s38, 31
	s_lshl_b32 s40, s36, 18
	s_lshl_b32 s41, s37, 7
	s_add_u32 s40, s40, s41
	s_add_u32 s12, s12, s40
	s_addc_u32 s13, s13, 0
	global_load_dwordx4 v[0:3], v124, s[12:13]
	global_load_dwordx4 v[4:7], v125, s[12:13]
	global_load_dwordx4 v[8:11], v126, s[12:13]
	global_load_dwordx4 v[12:15], v127, s[12:13]
	global_load_dwordx4 v[16:19], v128, s[12:13]
	global_load_dwordx4 v[20:23], v129, s[12:13]
	global_load_dwordx4 v[24:27], v130, s[12:13]
	global_load_dwordx4 v[28:31], v131, s[12:13]
	v_mov_b32_e32 v32, 1.0
	v_mov_b32_e32 v33, 1.0
	v_mov_b32_e32 v34, 1.0
	v_mov_b32_e32 v35, 1.0
	v_mov_b32_e32 v36, 1.0
	v_mov_b32_e32 v37, 1.0
	v_mov_b32_e32 v38, 1.0
	v_mov_b32_e32 v39, 1.0
	s_cmp_eq_u32 s33, 0
	s_cbranch_scc1 .Ltail_wnog
	s_lshl_b32 s40, s36, 8
	v_lshl_add_u32 v40, v123, 5, s40
	global_load_dwordx4 v[32:35], v40, s[6:7]
	global_load_dwordx4 v[36:39], v40, s[6:7] offset:16
.Ltail_wnog:
	s_lshl_b32 s40, s37, 5
	v_lshl_add_u32 v41, v122, 2, s40
	v_mul_lo_u32 v41, v41, s32
	s_lshl_b32 s40, s36, 6
	v_lshl_add_u32 v42, v123, 3, s40
	v_add_lshl_u32 v41, v41, v42, 1
	s_lshl_b32 s40, s32, 1
	s_waitcnt vmcnt(0)
	v_mul_f32_e32 v0, v0, v32
	v_mul_f32_e32 v1, v1, v32
	v_mul_f32_e32 v2, v2, v32
	v_mul_f32_e32 v3, v3, v32
	v_mul_f32_e32 v4, v4, v33
	v_mul_f32_e32 v5, v5, v33
	v_mul_f32_e32 v6, v6, v33
	v_mul_f32_e32 v7, v7, v33
	v_mul_f32_e32 v8, v8, v34
	v_mul_f32_e32 v9, v9, v34
	v_mul_f32_e32 v10, v10, v34
	v_mul_f32_e32 v11, v11, v34
	v_mul_f32_e32 v12, v12, v35
	v_mul_f32_e32 v13, v13, v35
	v_mul_f32_e32 v14, v14, v35
	v_mul_f32_e32 v15, v15, v35
	v_mul_f32_e32 v16, v16, v36
	v_mul_f32_e32 v17, v17, v36
	v_mul_f32_e32 v18, v18, v36
	v_mul_f32_e32 v19, v19, v36
	v_mul_f32_e32 v20, v20, v37
	v_mul_f32_e32 v21, v21, v37
	v_mul_f32_e32 v22, v22, v37
	v_mul_f32_e32 v23, v23, v37
	v_mul_f32_e32 v24, v24, v38
	v_mul_f32_e32 v25, v25, v38
	v_mul_f32_e32 v26, v26, v38
	v_mul_f32_e32 v27, v27, v38
	v_mul_f32_e32 v28, v28, v39
	v_mul_f32_e32 v29, v29, v39
	v_mul_f32_e32 v30, v30, v39
	v_mul_f32_e32 v31, v31, v39
	v_cvt_pk_bf16_f32 v44, v0, v4
	v_cvt_pk_bf16_f32 v45, v8, v12
	v_cvt_pk_bf16_f32 v46, v16, v20
	v_cvt_pk_bf16_f32 v47, v24, v28
	global_store_dwordx4 v41, v[44:47], s[14:15]
	v_add_u32_e32 v41, s40, v41
	v_cvt_pk_bf16_f32 v48, v1, v5
	v_cvt_pk_bf16_f32 v49, v9, v13
	v_cvt_pk_bf16_f32 v50, v17, v21
	v_cvt_pk_bf16_f32 v51, v25, v29
	global_store_dwordx4 v41, v[48:51], s[14:15]
	v_add_u32_e32 v41, s40, v41
	v_cvt_pk_bf16_f32 v52, v2, v6
	v_cvt_pk_bf16_f32 v53, v10, v14
	v_cvt_pk_bf16_f32 v54, v18, v22
	v_cvt_pk_bf16_f32 v55, v26, v30
	global_store_dwordx4 v41, v[52:55], s[14:15]
	v_add_u32_e32 v41, s40, v41
	v_cvt_pk_bf16_f32 v56, v3, v7
	v_cvt_pk_bf16_f32 v57, v11, v15
	v_cvt_pk_bf16_f32 v58, v19, v23
	v_cvt_pk_bf16_f32 v59, v27, v31
	global_store_dwordx4 v41, v[56:59], s[14:15]
	s_add_u32 s39, s39, 0x2a0
	s_branch .Ltail_w
.Ltail_w_done:
.Ltail_done:
	s_waitcnt vmcnt(0)
	s_waitcnt lgkmcnt(0)
	s_barrier
	s_and_saveexec_b64 s[6:7], s[72:73]
	s_cbranch_execz .LBB0_760
	s_add_i32 s0, 0, 0x22c00
	v_mov_b32_e32 v0, s0
	s_waitcnt vmcnt(0) expcnt(0) lgkmcnt(0)
	ds_read_b32 v2, v0
	s_add_i32 s0, 0, 0x22c04
	v_mov_b32_e32 v0, s0
	ds_read_b32 v0, v0
	s_waitcnt lgkmcnt(1)
	v_cmp_ne_u32_e32 vcc, 0, v2
	s_cbranch_vccnz .LBB0_724
	s_add_u32 s8, s64, 0x1b00200
	s_addc_u32 s9, s65, 0
	s_add_u32 s10, s64, 0x1b00400
	s_addc_u32 s11, s65, 0
	s_add_u32 s12, s64, 0x1b00500
	s_addc_u32 s13, s65, 0
	s_add_u32 s14, s64, 0x1b00600
	s_addc_u32 s15, s65, 0
	s_add_u32 s16, s64, 0x1b00700
	s_addc_u32 s17, s65, 0
	s_add_u32 s18, s64, 0x1b00800
	s_addc_u32 s19, s65, 0
	s_add_u32 s20, s64, 0x1b00900
	s_addc_u32 s21, s65, 0
	s_add_u32 s22, s64, 0x1b00a00
	s_addc_u32 s23, s65, 0
	s_add_u32 s24, s64, 0x1b00b00
	s_addc_u32 s25, s65, 0
	s_add_u32 s26, s64, 0x1b00c00
	s_addc_u32 s27, s65, 0
	s_add_u32 s28, s64, 0x1b00d00
	s_addc_u32 s29, s65, 0
	s_add_u32 s30, s64, 0x1b00e00
	s_addc_u32 s31, s65, 0
	s_add_u32 s34, s64, 0x1b00f00
	s_addc_u32 s35, s65, 0
	s_add_u32 s36, s64, 0x1b01000
	s_addc_u32 s37, s65, 0
	s_add_u32 s38, s64, 0x1b01100
	s_addc_u32 s39, s65, 0
	s_add_u32 s40, s64, 0x1b01200
	s_addc_u32 s41, s65, 0
	s_mul_i32 s0, s67, s77
	s_add_u32 s42, s64, 0x1b01300
	s_mul_i32 s0, s0, s66
	s_addc_u32 s43, s65, 0
	s_mov_b32 s1, 1
	v_mov_b32_e32 v16, 0
	s_branch .LBB0_712
